# attention: -mrun splat kept in dedicated VGPR block (refresh only on rescale), drop per-tile v_mov copies; P12 loop hand-pipelined
# speedup vs baseline: 1.0081x; 1.0081x over previous
.LBB0_737:
	s_or_b64 exec, exec, s[4:5]
	global_load_dwordx4 v[132:135], v[12:13], off offset:128
	v_add_u32_e32 v0, v178, v148
	s_waitcnt vmcnt(1)
	ds_write_b128 v0, v[128:131] offset:22016
	s_and_saveexec_b64 s[4:5], s[2:3]
	ds_write_b128 v186, v[124:127] offset:22144
	s_or_b64 exec, exec, s[4:5]
	s_waitcnt vmcnt(0)
	ds_write2_b64 v149, v[132:133], v[134:135] offset1:1
	s_waitcnt lgkmcnt(0)
	s_barrier
	ds_read_b128 v[0:3], v185
	ds_read_b128 v[4:7], v185 offset:32
	s_waitcnt lgkmcnt(1)
	v_mfma_f32_32x32x16_bf16 v[48:63], v[0:3], v[100:103], 0
	s_mov_b32 s4, 0
	s_mov_b32 s5, s4
	s_mov_b32 s6, s4
	s_mov_b32 s7, s4
	s_mov_b32 s8, s4
	s_mov_b32 s9, s4
	s_mov_b32 s10, s4
	s_waitcnt lgkmcnt(0)
	v_mfma_f32_32x32x16_bf16 v[48:63], v[4:7], v[104:107], v[48:63]
	ds_read_b128 v[0:3], v185 offset:64
	ds_read_b128 v[4:7], v185 offset:96
	s_mov_b32 s11, s4
	s_mov_b32 s12, s4
	s_mov_b32 s13, s4
	s_mov_b32 s14, s4
	s_mov_b32 s15, s4
	s_mov_b32 s16, s4
	s_waitcnt lgkmcnt(1)
	v_mfma_f32_32x32x16_bf16 v[48:63], v[0:3], v[108:111], v[48:63]
	s_mov_b32 s17, s4
	s_mov_b32 s18, s4
	s_mov_b32 s19, s4
	s_waitcnt lgkmcnt(0)
	v_mfma_f32_32x32x16_bf16 v[48:63], v[4:7], v[112:115], v[48:63]
	ds_read_b128 v[0:3], v185 offset:128
	ds_read_b128 v[4:7], v185 offset:160
	s_waitcnt lgkmcnt(1)
	v_mfma_f32_32x32x16_bf16 v[48:63], v[0:3], v[116:119], v[48:63]
	s_waitcnt lgkmcnt(0)
	v_mfma_f32_32x32x16_bf16 v[48:63], v[4:7], v[120:123], v[48:63]
	ds_read_b128 v[0:3], v185 offset:6656
	ds_read_b128 v[4:7], v185 offset:6688
	s_waitcnt lgkmcnt(1)
	v_mfma_f32_32x32x16_bf16 v[32:47], v[0:3], v[100:103], 0
	s_waitcnt lgkmcnt(0)
	v_mfma_f32_32x32x16_bf16 v[32:47], v[4:7], v[104:107], v[32:47]
	ds_read_b128 v[0:3], v185 offset:6720
	ds_read_b128 v[4:7], v185 offset:6752
	ds_read_b128 v[16:19], v185 offset:6816
	s_waitcnt lgkmcnt(2)
	v_mfma_f32_32x32x16_bf16 v[32:47], v[0:3], v[108:111], v[32:47]
	ds_read_b128 v[0:3], v185 offset:6784
	s_waitcnt lgkmcnt(2)
	v_mfma_f32_32x32x16_bf16 v[32:47], v[4:7], v[112:115], v[32:47]
	s_waitcnt lgkmcnt(0)
	v_mfma_f32_32x32x16_bf16 v[32:47], v[0:3], v[116:119], v[32:47]
	v_mov_b64_e32 v[0:1], s[4:5]
	v_mov_b64_e32 v[2:3], s[6:7]
	v_mov_b64_e32 v[4:5], s[8:9]
	v_mov_b64_e32 v[6:7], s[10:11]
	v_mov_b64_e32 v[8:9], s[12:13]
	v_mov_b64_e32 v[10:11], s[14:15]
	v_mov_b64_e32 v[12:13], s[16:17]
	v_mfma_f32_32x32x16_bf16 v[32:47], v[16:19], v[120:123], v[32:47]
	v_mov_b64_e32 v[14:15], s[18:19]
	s_nop 15
	s_nop 15
	s_nop 15
	v_mov_b64_e32 v[30:31], v[14:15]
	v_lshl_add_u64 v[98:99], v[152:153], 0, s[34:35]
	v_lshl_add_u64 v[168:169], v[146:147], 0, s[0:1]
	v_lshl_add_u64 v[170:171], v[154:155], 0, s[0:1]
	v_mov_b32_e32 v157, 0
	v_mov_b64_e32 v[28:29], v[12:13]
	v_mov_b64_e32 v[26:27], v[10:11]
	v_mov_b64_e32 v[24:25], v[8:9]
	v_mov_b64_e32 v[22:23], v[6:7]
	v_mov_b64_e32 v[20:21], v[4:5]
	v_mov_b64_e32 v[18:19], v[2:3]
	v_mov_b64_e32 v[16:17], v[0:1]
	v_mov_b32_e32 v96, 0
	v_mov_b32_e32 v228, 0x80000000
	v_mov_b32_e32 v229, v228
	v_mov_b32_e32 v230, v228
	v_mov_b32_e32 v231, v228
	v_mov_b32_e32 v232, v228
	v_mov_b32_e32 v233, v228
	v_mov_b32_e32 v234, v228
	v_mov_b32_e32 v235, v228
	v_mov_b32_e32 v236, v228
	v_mov_b32_e32 v237, v228
	v_mov_b32_e32 v238, v228
	v_mov_b32_e32 v239, v228
	v_mov_b32_e32 v240, v228
	v_mov_b32_e32 v241, v228
	v_mov_b32_e32 v242, v228
	v_mov_b32_e32 v243, v228

.LBB0_744:
	v_max3_f32 v64, v48, v49, v50
	s_cmp_eq_u32 s4, 0
	v_max3_f32 v64, v64, v51, v52
	s_cselect_b64 s[0:1], -1, 0
	v_max3_f32 v64, v64, v53, v54
	v_max3_f32 v64, v64, v55, v56
	v_max3_f32 v64, v64, v57, v58
	v_max3_f32 v64, v64, v59, v60
	v_max3_f32 v64, v64, v61, v62
	v_max3_f32 v64, v64, v63, v194
	v_max3_f32 v64, v64, v33, v34
	v_max3_f32 v64, v64, v35, v36
	v_max3_f32 v64, v64, v37, v38
	v_max3_f32 v64, v64, v39, v40
	v_max3_f32 v64, v64, v41, v42
	v_max3_f32 v64, v64, v43, v44
	v_max3_f32 v64, v64, v45, v46
	v_max3_f32 v64, v64, v159, v159
	v_mov_b32_e32 v65, v64
	s_nop 1
	v_permlane32_swap_b32_e32 v64, v65
	v_cmp_lt_f32_e32 vcc, s42, v64
	s_or_b64 vcc, s[0:1], vcc
	s_cbranch_vccz .LBB0_746
	v_max_f32_e32 v65, v64, v64
	v_max_f32_e32 v65, 0, v65
	v_cndmask_b32_e64 v65, v65, v64, s[0:1]
	v_exp_f32_e64 v64, -v65
	v_add_f32_e32 v96, v96, v65
	v_sub_f32_e32 v48, v48, v65
	v_sub_f32_e32 v49, v49, v65
	v_cndmask_b32_e64 v64, v64, 1.0, s[0:1]
	v_mul_f32_e32 v157, v157, v64
	v_sub_f32_e32 v50, v50, v65
	v_sub_f32_e32 v63, v63, v65
	v_sub_f32_e32 v51, v51, v65
	v_sub_f32_e32 v52, v52, v65
	v_sub_f32_e32 v53, v53, v65
	v_sub_f32_e32 v54, v54, v65
	v_sub_f32_e32 v55, v55, v65
	v_sub_f32_e32 v56, v56, v65
	v_sub_f32_e32 v57, v57, v65
	v_sub_f32_e32 v58, v58, v65
	v_sub_f32_e32 v59, v59, v65
	v_sub_f32_e32 v60, v60, v65
	v_sub_f32_e32 v61, v61, v65
	v_sub_f32_e32 v62, v62, v65
	v_sub_f32_e32 v194, v32, v65
	v_sub_f32_e32 v159, v47, v65
	v_sub_f32_e32 v195, v33, v65
	v_sub_f32_e32 v196, v34, v65
	v_sub_f32_e32 v198, v35, v65
	v_sub_f32_e32 v200, v36, v65
	v_sub_f32_e32 v197, v37, v65
	v_sub_f32_e32 v199, v38, v65
	v_sub_f32_e32 v201, v39, v65
	v_sub_f32_e32 v161, v40, v65
	v_sub_f32_e32 v188, v41, v65
	v_sub_f32_e32 v189, v42, v65
	v_sub_f32_e32 v190, v43, v65
	v_sub_f32_e32 v191, v44, v65
	v_sub_f32_e32 v192, v45, v65
	v_sub_f32_e32 v193, v46, v65
	v_pk_mul_f32 v[14:15], v[14:15], v[64:65] op_sel_hi:[1,0]
	v_pk_mul_f32 v[12:13], v[12:13], v[64:65] op_sel_hi:[1,0]
	v_pk_mul_f32 v[10:11], v[10:11], v[64:65] op_sel_hi:[1,0]
	v_pk_mul_f32 v[8:9], v[8:9], v[64:65] op_sel_hi:[1,0]
	v_pk_mul_f32 v[6:7], v[6:7], v[64:65] op_sel_hi:[1,0]
	v_pk_mul_f32 v[4:5], v[4:5], v[64:65] op_sel_hi:[1,0]
	v_pk_mul_f32 v[2:3], v[2:3], v[64:65] op_sel_hi:[1,0]
	v_pk_mul_f32 v[0:1], v[0:1], v[64:65] op_sel_hi:[1,0]
	v_pk_mul_f32 v[30:31], v[30:31], v[64:65] op_sel_hi:[1,0]
	v_pk_mul_f32 v[28:29], v[28:29], v[64:65] op_sel_hi:[1,0]
	v_pk_mul_f32 v[26:27], v[26:27], v[64:65] op_sel_hi:[1,0]
	v_pk_mul_f32 v[24:25], v[24:25], v[64:65] op_sel_hi:[1,0]
	v_pk_mul_f32 v[22:23], v[22:23], v[64:65] op_sel_hi:[1,0]
	v_pk_mul_f32 v[20:21], v[20:21], v[64:65] op_sel_hi:[1,0]
	v_pk_mul_f32 v[18:19], v[18:19], v[64:65] op_sel_hi:[1,0]
	v_pk_mul_f32 v[16:17], v[16:17], v[64:65] op_sel_hi:[1,0]
	v_xor_b32_e32 v228, 0x80000000, v96
	v_mov_b32_e32 v229, v228
	v_mov_b32_e32 v230, v228
	v_mov_b32_e32 v231, v228
	v_mov_b32_e32 v232, v228
	v_mov_b32_e32 v233, v228
	v_mov_b32_e32 v234, v228
	v_mov_b32_e32 v235, v228
	v_mov_b32_e32 v236, v228
	v_mov_b32_e32 v237, v228
	v_mov_b32_e32 v238, v228
	v_mov_b32_e32 v239, v228
	v_mov_b32_e32 v240, v228
	v_mov_b32_e32 v241, v228
	v_mov_b32_e32 v242, v228
	v_mov_b32_e32 v243, v228
.LBB0_746:
	s_or_b32 s1, s4, 1
	s_and_b32 s5, s1, 0xff
	s_mulk_i32 s5, 0xab
	s_mul_i32 s0, s4, 0xab
	s_bfe_u32 s5, s5, 0x70009
	s_bfe_u32 s0, s0, 0x70009
	s_mul_i32 s5, s5, 3
	s_mul_i32 s0, s0, 3
	s_sub_i32 s1, s1, s5
	s_add_i32 s5, s4, 2
	s_sub_i32 s0, s4, s0
	s_mul_i32 s10, s5, 0xab
	s_and_b32 s0, s0, 0xff
	s_bfe_u32 s10, s10, 0x70009
	s_and_b32 s1, s1, 0xff
	s_mul_i32 s10, s10, 3
	s_mulk_i32 s0, 0x5600
	s_sub_i32 s10, s5, s10
	s_mulk_i32 s1, 0x5600
	s_add_i32 s0, s0, 0
	s_and_b32 s11, s10, 0xff
	s_add_i32 s10, s1, 0
	v_add3_u32 v44, s0, v182, v136
	v_add3_u32 v223, s10, v181, v179
	v_add_u32_e32 v224, 0x3000, v44
	v_add3_u32 v44, s0, v183, v136
	v_add3_u32 v222, s10, v180, v179
	ds_read_b128 v[202:205], v223
	ds_read_b128 v[64:67], v222
	ds_read_b128 v[68:71], v222 offset:32
	v_add_u32_e32 v225, 0x3000, v44
	ds_read2_b64 v[72:75], v224 offset0:128 offset1:130
	ds_read2_b64 v[76:79], v225 offset0:128 offset1:130
	s_waitcnt lgkmcnt(3)
	s_nop 0
	v_mfma_f32_32x32x16_bf16 v[80:95], v[64:67], v[100:103], v[228:243]
	v_exp_f32_e32 v226, v48
	v_exp_f32_e32 v49, v49
	v_exp_f32_e32 v227, v50
	v_exp_f32_e32 v245, v51
	v_exp_f32_e32 v246, v52
	v_exp_f32_e32 v54, v54
	v_exp_f32_e32 v55, v55
	s_waitcnt lgkmcnt(2)
	v_mfma_f32_32x32x16_bf16 v[80:95], v[68:71], v[104:107], v[80:95]
	v_exp_f32_e32 v68, v53
	v_cvt_pk_bf16_f32 v50, v226, v49
	v_cvt_pk_bf16_f32 v51, v227, v245
	v_cvt_pk_bf16_f32 v53, v54, v55
	v_cvt_pk_bf16_f32 v52, v246, v68
	ds_read_b128 v[64:67], v222 offset:64
	ds_read_b128 v[206:209], v223 offset:32
	ds_read_b128 v[210:213], v223 offset:64
	ds_read2_b64 v[214:217], v224 offset0:132 offset1:134
	ds_read2_b64 v[218:221], v225 offset0:132 offset1:134
	v_mov_b32_e32 v48, 0
	s_waitcnt lgkmcnt(6)
	v_mfma_f32_32x32x16_bf16 v[0:15], v[72:75], v[50:53], v[0:15]
	v_add_f32 v48, v48, v226
	v_add_f32 v48, v48, v49
	v_add_f32 v48, v48, v227
	v_add_f32 v48, v48, v245
	v_add_f32 v48, v48, v246
	v_add_f32 v48, v48, v68
	v_add_f32 v48, v48, v54
	v_add_f32 v48, v48, v55
	s_waitcnt lgkmcnt(5)
	v_mfma_f32_32x32x16_bf16 v[16:31], v[76:79], v[50:53], v[16:31]
	s_waitcnt lgkmcnt(4)
	v_mfma_f32_32x32x16_bf16 v[80:95], v[64:67], v[108:111], v[80:95]
	v_exp_f32_e32 v33, v56
	v_exp_f32_e32 v46, v57
	v_mfma_f32_32x32x16_bf16 v[64:79], v[202:205], v[100:103], v[228:243]
	v_exp_f32_e32 v47, v58
	v_exp_f32_e32 v49, v59
	v_exp_f32_e32 v202, v60
	v_exp_f32_e32 v203, v61
	v_exp_f32_e32 v62, v62
	v_exp_f32_e32 v63, v63
	v_cvt_pk_bf16_f32 v34, v33, v46
	v_cvt_pk_bf16_f32 v35, v47, v49
	v_cvt_pk_bf16_f32 v36, v202, v203
	v_cvt_pk_bf16_f32 v37, v62, v63
	s_waitcnt lgkmcnt(3)
	v_mfma_f32_32x32x16_bf16 v[64:79], v[206:209], v[104:107], v[64:79]
	ds_read_b128 v[38:41], v223 offset:96
	ds_read_b128 v[42:45], v222 offset:96
	ds_read_b128 v[50:53], v222 offset:128
	ds_read2_b64 v[54:57], v224 offset0:136 offset1:138
	ds_read2_b64 v[58:61], v225 offset0:136 offset1:138
	v_add_f32 v48, v48, v33
	v_add_f32 v48, v48, v46
	v_add_f32 v48, v48, v47
	v_add_f32 v48, v48, v49
	v_add_f32 v48, v48, v202
	v_add_f32 v48, v48, v203
	v_add_f32 v48, v48, v62
	v_add_f32 v48, v48, v63
	s_waitcnt lgkmcnt(6)
	v_mfma_f32_32x32x16_bf16 v[0:15], v[214:217], v[34:37], v[0:15]
	s_waitcnt lgkmcnt(5)
	v_mfma_f32_32x32x16_bf16 v[16:31], v[218:221], v[34:37], v[16:31]
	s_waitcnt lgkmcnt(3)
	v_mfma_f32_32x32x16_bf16 v[80:95], v[42:45], v[112:115], v[80:95]
	v_exp_f32_e32 v33, v194
	v_exp_f32_e32 v46, v195
	v_exp_f32_e32 v47, v196
	v_exp_f32_e32 v49, v198
	v_exp_f32_e32 v62, v200
	v_exp_f32_e32 v63, v197
	v_exp_f32_e32 v202, v199
	v_exp_f32_e32 v203, v201
	v_cvt_pk_bf16_f32 v34, v33, v46
	v_cvt_pk_bf16_f32 v35, v47, v49
	v_cvt_pk_bf16_f32 v36, v62, v63
	v_cvt_pk_bf16_f32 v37, v202, v203
	v_mfma_f32_32x32x16_bf16 v[64:79], v[210:213], v[108:111], v[64:79]
	s_waitcnt lgkmcnt(2)
	v_mfma_f32_32x32x16_bf16 v[80:95], v[50:53], v[116:119], v[80:95]
	s_waitcnt lgkmcnt(1)
	v_mfma_f32_32x32x16_bf16 v[0:15], v[54:57], v[34:37], v[0:15]
	ds_read_b128 v[42:45], v222 offset:160
	ds_read_b128 v[50:53], v223 offset:128
	ds_read_b128 v[54:57], v223 offset:160
	ds_read2_b64 v[194:197], v224 offset0:140 offset1:142
	ds_read2_b64 v[198:201], v225 offset0:140 offset1:142
	v_add_f32 v48, v48, v33
	v_add_f32 v48, v48, v46
	v_add_f32 v48, v48, v47
	v_add_f32 v48, v48, v49
	v_add_f32 v48, v48, v62
	v_add_f32 v48, v48, v63
	v_add_f32 v48, v48, v202
	v_add_f32 v48, v48, v203
	s_waitcnt lgkmcnt(5)
	v_mfma_f32_32x32x16_bf16 v[16:31], v[58:61], v[34:37], v[16:31]
	v_mfma_f32_32x32x16_bf16 v[64:79], v[38:41], v[112:115], v[64:79]
	v_exp_f32_e32 v33, v161
	v_exp_f32_e32 v38, v188
	v_exp_f32_e32 v39, v189
	v_exp_f32_e32 v40, v190
	v_exp_f32_e32 v41, v191
	v_cvt_pk_bf16_f32 v34, v33, v38
	v_cvt_pk_bf16_f32 v35, v39, v40
	s_waitcnt lgkmcnt(3)
	v_mfma_f32_32x32x16_bf16 v[64:79], v[50:53], v[116:119], v[64:79]
	v_mfma_f32_32x32x16_bf16 v[80:95], v[42:45], v[120:123], v[80:95]
	v_exp_f32_e32 v42, v192
	v_exp_f32_e32 v43, v193
	v_exp_f32_e32 v44, v159
	v_add_f32 v48, v48, v33
	v_add_f32 v48, v48, v38
	v_add_f32 v48, v48, v39
	v_add_f32 v48, v48, v40
	v_add_f32 v48, v48, v41
	v_add_f32 v48, v48, v42
	v_add_f32 v48, v48, v43
	v_add_f32 v48, v48, v44
	v_cvt_pk_bf16_f32 v36, v41, v42
	v_cvt_pk_bf16_f32 v37, v43, v44
	s_waitcnt lgkmcnt(2)
	v_mfma_f32_32x32x16_bf16 v[64:79], v[54:57], v[120:123], v[64:79]
	s_waitcnt lgkmcnt(1)
	v_mfma_f32_32x32x16_bf16 v[0:15], v[194:197], v[34:37], v[0:15]
	s_waitcnt lgkmcnt(0)
	v_mfma_f32_32x32x16_bf16 v[16:31], v[198:201], v[34:37], v[16:31]
	s_andn2_b64 vcc, exec, s[8:9]
	s_mulk_i32 s11, 0x5600
	s_cbranch_vccnz .LBB0_750
	s_add_i32 s8, s11, 0
	v_add3_u32 v33, s8, v141, v148
	s_waitcnt vmcnt(1)
	ds_write_b128 v33, v[128:131]
	s_and_saveexec_b64 s[0:1], s[2:3]
	v_add3_u32 v33, s8, v174, v175
	ds_write_b128 v33, v[124:127] offset:128
	s_or_b64 exec, exec, s[0:1]
	v_add_u32_e32 v33, s8, v176
	v_add3_u32 v33, v33, v148, s41
	s_waitcnt vmcnt(0)
	ds_write2_b64 v33, v[132:133], v[134:135] offset1:1

.LBB0_754:
	v_max3_f32 v33, v80, v81, v82
	v_add_f32_e32 v157, v157, v48
	v_max3_f32 v33, v33, v83, v84
	v_max3_f32 v33, v33, v85, v86
	v_max3_f32 v33, v33, v87, v88
	v_max3_f32 v33, v33, v89, v90
	v_max3_f32 v33, v33, v91, v92
	v_max3_f32 v33, v33, v93, v94
	v_max3_f32 v33, v33, v95, v64
	v_max3_f32 v33, v33, v65, v66
	v_max3_f32 v33, v33, v67, v68
	v_max3_f32 v33, v33, v69, v70
	v_max3_f32 v33, v33, v71, v72
	v_max3_f32 v33, v33, v73, v74
	v_max3_f32 v33, v33, v75, v76
	v_max3_f32 v33, v33, v77, v78
	v_max3_f32 v33, v33, v79, v79
	v_mov_b32_e32 v34, v33
	s_nop 1
	v_permlane32_swap_b32_e32 v33, v34
	v_cmp_lt_f32_e32 vcc, s42, v33
	s_cbranch_vccz .LBB0_756
	v_max_f32_e32 v32, v33, v33
	v_max_f32_e32 v33, 0, v32
	v_exp_f32_e64 v32, -v33
	v_add_f32_e32 v96, v96, v33
	v_sub_f32_e32 v83, v83, v33
	v_sub_f32_e32 v84, v84, v33
	v_mul_f32_e32 v157, v157, v32
	v_sub_f32_e32 v85, v85, v33
	v_sub_f32_e32 v86, v86, v33
	v_sub_f32_e32 v87, v87, v33
	v_sub_f32_e32 v88, v88, v33
	v_sub_f32_e32 v89, v89, v33
	v_sub_f32_e32 v90, v90, v33
	v_sub_f32_e32 v91, v91, v33
	v_sub_f32_e32 v92, v92, v33
	v_sub_f32_e32 v93, v93, v33
	v_sub_f32_e32 v94, v94, v33
	v_sub_f32_e32 v80, v80, v33
	v_sub_f32_e32 v81, v81, v33
	v_sub_f32_e32 v82, v82, v33
	v_sub_f32_e32 v95, v95, v33
	v_sub_f32_e32 v65, v65, v33
	v_sub_f32_e32 v66, v66, v33
	v_sub_f32_e32 v67, v67, v33
	v_sub_f32_e32 v68, v68, v33
	v_sub_f32_e32 v69, v69, v33
	v_sub_f32_e32 v70, v70, v33
	v_sub_f32_e32 v71, v71, v33
	v_sub_f32_e32 v72, v72, v33
	v_sub_f32_e32 v73, v73, v33
	v_sub_f32_e32 v74, v74, v33
	v_sub_f32_e32 v75, v75, v33
	v_sub_f32_e32 v76, v76, v33
	v_sub_f32_e32 v77, v77, v33
	v_sub_f32_e32 v78, v78, v33
	v_sub_f32_e32 v64, v64, v33
	v_sub_f32_e32 v79, v79, v33
	v_pk_mul_f32 v[14:15], v[14:15], v[32:33] op_sel_hi:[1,0]
	v_pk_mul_f32 v[12:13], v[12:13], v[32:33] op_sel_hi:[1,0]
	v_pk_mul_f32 v[10:11], v[10:11], v[32:33] op_sel_hi:[1,0]
	v_pk_mul_f32 v[8:9], v[8:9], v[32:33] op_sel_hi:[1,0]
	v_pk_mul_f32 v[6:7], v[6:7], v[32:33] op_sel_hi:[1,0]
	v_pk_mul_f32 v[4:5], v[4:5], v[32:33] op_sel_hi:[1,0]
	v_pk_mul_f32 v[2:3], v[2:3], v[32:33] op_sel_hi:[1,0]
	v_pk_mul_f32 v[0:1], v[0:1], v[32:33] op_sel_hi:[1,0]
	v_pk_mul_f32 v[30:31], v[30:31], v[32:33] op_sel_hi:[1,0]
	v_pk_mul_f32 v[28:29], v[28:29], v[32:33] op_sel_hi:[1,0]
	v_pk_mul_f32 v[26:27], v[26:27], v[32:33] op_sel_hi:[1,0]
	v_pk_mul_f32 v[24:25], v[24:25], v[32:33] op_sel_hi:[1,0]
	v_pk_mul_f32 v[22:23], v[22:23], v[32:33] op_sel_hi:[1,0]
	v_pk_mul_f32 v[20:21], v[20:21], v[32:33] op_sel_hi:[1,0]
	v_pk_mul_f32 v[18:19], v[18:19], v[32:33] op_sel_hi:[1,0]
	v_pk_mul_f32 v[16:17], v[16:17], v[32:33] op_sel_hi:[1,0]
	v_xor_b32_e32 v228, 0x80000000, v96
	v_mov_b32_e32 v229, v228
	v_mov_b32_e32 v230, v228
	v_mov_b32_e32 v231, v228
	v_mov_b32_e32 v232, v228
	v_mov_b32_e32 v233, v228
	v_mov_b32_e32 v234, v228
	v_mov_b32_e32 v235, v228
	v_mov_b32_e32 v236, v228
	v_mov_b32_e32 v237, v228
	v_mov_b32_e32 v238, v228
	v_mov_b32_e32 v239, v228
	v_mov_b32_e32 v240, v228
	v_mov_b32_e32 v241, v228
	v_mov_b32_e32 v242, v228
	v_mov_b32_e32 v243, v228
.LBB0_756:
	s_add_i32 s8, s11, 0
	v_add3_u32 v161, s8, v181, v179
	v_add3_u32 v44, s10, v182, v136
	v_add3_u32 v159, s8, v180, v179
	ds_read_b128 v[188:191], v161
	ds_read_b128 v[192:195], v159
	ds_read_b128 v[196:199], v159 offset:32
	v_add_u32_e32 v172, 0x3000, v44
	v_add3_u32 v44, s10, v183, v136
	v_add_u32_e32 v173, 0x3000, v44
	ds_read2_b64 v[200:203], v172 offset0:128 offset1:130
	ds_read2_b64 v[204:207], v173 offset0:128 offset1:130
	s_waitcnt lgkmcnt(3)
	s_nop 0
	v_mfma_f32_32x32x16_bf16 v[48:63], v[192:195], v[100:103], v[228:243]
	v_exp_f32_e32 v216, v80
	v_exp_f32_e32 v81, v81
	v_exp_f32_e32 v217, v82
	v_exp_f32_e32 v218, v83
	v_exp_f32_e32 v219, v84
	v_exp_f32_e32 v220, v85
	v_exp_f32_e32 v86, v86
	v_exp_f32_e32 v87, v87
	v_cvt_pk_bf16_f32 v82, v216, v81
	v_cvt_pk_bf16_f32 v83, v217, v218
	v_cvt_pk_bf16_f32 v84, v219, v220
	v_cvt_pk_bf16_f32 v85, v86, v87
	s_waitcnt lgkmcnt(2)
	v_mfma_f32_32x32x16_bf16 v[48:63], v[196:199], v[104:107], v[48:63]
	v_mov_b32_e32 v80, 0
	s_waitcnt lgkmcnt(1)
	v_mfma_f32_32x32x16_bf16 v[0:15], v[200:203], v[82:85], v[0:15]
	ds_read_b128 v[192:195], v159 offset:64
	ds_read_b128 v[196:199], v161 offset:32
	ds_read_b128 v[200:203], v161 offset:64
	ds_read2_b64 v[208:211], v172 offset0:132 offset1:134
	ds_read2_b64 v[212:215], v173 offset0:132 offset1:134
	v_add_f32 v80, v80, v216
	v_add_f32 v80, v80, v81
	v_add_f32 v80, v80, v217
	v_add_f32 v80, v80, v218
	v_add_f32 v80, v80, v219
	v_add_f32 v80, v80, v220
	v_add_f32 v80, v80, v86
	v_add_f32 v80, v80, v87
	s_waitcnt lgkmcnt(5)
	v_mfma_f32_32x32x16_bf16 v[16:31], v[204:207], v[82:85], v[16:31]
	v_mfma_f32_32x32x16_bf16 v[32:47], v[188:191], v[100:103], v[228:243]
	v_exp_f32_e32 v81, v88
	v_exp_f32_e32 v204, v89
	v_exp_f32_e32 v205, v90
	v_exp_f32_e32 v206, v91
	v_exp_f32_e32 v207, v92
	v_exp_f32_e32 v216, v93
	v_exp_f32_e32 v94, v94
	v_exp_f32_e32 v95, v95
	v_cvt_pk_bf16_f32 v82, v81, v204
	v_cvt_pk_bf16_f32 v83, v205, v206
	v_cvt_pk_bf16_f32 v84, v207, v216
	v_cvt_pk_bf16_f32 v85, v94, v95
	s_waitcnt lgkmcnt(4)
	v_mfma_f32_32x32x16_bf16 v[48:63], v[192:195], v[108:111], v[48:63]
	s_waitcnt lgkmcnt(3)
	v_mfma_f32_32x32x16_bf16 v[32:47], v[196:199], v[104:107], v[32:47]
	ds_read_b128 v[86:89], v161 offset:96
	ds_read_b128 v[90:93], v159 offset:96
	ds_read_b128 v[188:191], v159 offset:128
	ds_read2_b64 v[192:195], v172 offset0:136 offset1:138
	ds_read2_b64 v[196:199], v173 offset0:136 offset1:138
	v_add_f32 v80, v80, v81
	v_add_f32 v80, v80, v204
	v_add_f32 v80, v80, v205
	v_add_f32 v80, v80, v206
	v_add_f32 v80, v80, v207
	v_add_f32 v80, v80, v216
	v_add_f32 v80, v80, v94
	v_add_f32 v80, v80, v95
	s_waitcnt lgkmcnt(6)
	v_mfma_f32_32x32x16_bf16 v[0:15], v[208:211], v[82:85], v[0:15]
	s_waitcnt lgkmcnt(5)
	v_mfma_f32_32x32x16_bf16 v[16:31], v[212:215], v[82:85], v[16:31]
	s_waitcnt lgkmcnt(3)
	v_mfma_f32_32x32x16_bf16 v[48:63], v[90:93], v[112:115], v[48:63]
	v_exp_f32_e32 v81, v64
	v_exp_f32_e32 v94, v65
	v_exp_f32_e32 v95, v66
	v_exp_f32_e32 v204, v71
	v_cvt_pk_bf16_f32 v64, v81, v94
	v_mfma_f32_32x32x16_bf16 v[32:47], v[200:203], v[108:111], v[32:47]
	v_exp_f32_e32 v200, v67
	v_exp_f32_e32 v201, v68
	v_exp_f32_e32 v202, v69
	v_exp_f32_e32 v203, v70
	v_cvt_pk_bf16_f32 v65, v95, v200
	v_cvt_pk_bf16_f32 v66, v201, v202
	v_cvt_pk_bf16_f32 v67, v203, v204
	v_mfma_f32_32x32x16_bf16 v[32:47], v[86:89], v[112:115], v[32:47]
	s_waitcnt lgkmcnt(2)
	v_mfma_f32_32x32x16_bf16 v[48:63], v[188:191], v[116:119], v[48:63]
	ds_read_b128 v[68:71], v159 offset:160
	ds_read_b128 v[82:85], v161 offset:128
	ds_read_b128 v[86:89], v161 offset:160
	ds_read2_b64 v[90:93], v172 offset0:140 offset1:142
	ds_read2_b64 v[188:191], v173 offset0:140 offset1:142
	v_add_f32 v80, v80, v81
	v_add_f32 v80, v80, v94
	v_add_f32 v80, v80, v95
	v_add_f32 v80, v80, v200
	v_add_f32 v80, v80, v201
	v_add_f32 v80, v80, v202
	v_add_f32 v80, v80, v203
	v_add_f32 v80, v80, v204
	s_waitcnt lgkmcnt(6)
	v_mfma_f32_32x32x16_bf16 v[0:15], v[192:195], v[64:67], v[0:15]
	s_waitcnt lgkmcnt(5)
	v_mfma_f32_32x32x16_bf16 v[16:31], v[196:199], v[64:67], v[16:31]
	s_waitcnt lgkmcnt(3)
	v_mfma_f32_32x32x16_bf16 v[32:47], v[82:85], v[116:119], v[32:47]
	v_mfma_f32_32x32x16_bf16 v[48:63], v[68:71], v[120:123], v[48:63]
	v_exp_f32_e32 v68, v72
	v_exp_f32_e32 v69, v73
	v_exp_f32_e32 v70, v74
	v_exp_f32_e32 v71, v75
	v_exp_f32_e32 v72, v76
	v_exp_f32_e32 v73, v77
	v_exp_f32_e32 v74, v78
	v_exp_f32_e32 v75, v79
	v_cvt_pk_bf16_f32 v64, v68, v69
	v_cvt_pk_bf16_f32 v65, v70, v71
	v_cvt_pk_bf16_f32 v66, v72, v73
	v_cvt_pk_bf16_f32 v67, v74, v75
	s_waitcnt lgkmcnt(2)
	v_mfma_f32_32x32x16_bf16 v[32:47], v[86:89], v[120:123], v[32:47]
	v_add_f32 v80, v80, v68
	v_add_f32 v80, v80, v69
	v_add_f32 v80, v80, v70
	v_add_f32 v80, v80, v71
	v_add_f32 v80, v80, v72
	v_add_f32 v80, v80, v73
	v_add_f32 v80, v80, v74
	v_add_f32 v80, v80, v75
	s_waitcnt lgkmcnt(1)
	v_mfma_f32_32x32x16_bf16 v[0:15], v[90:93], v[64:67], v[0:15]
	s_waitcnt lgkmcnt(0)
	v_mfma_f32_32x32x16_bf16 v[16:31], v[188:191], v[64:67], v[16:31]
	s_andn2_b64 vcc, exec, s[0:1]
	s_cbranch_vccnz .LBB0_760
	s_add_i32 s0, s4, 3
	s_mul_i32 s1, s0, 0xab
	s_bfe_u32 s1, s1, 0x70009
	s_mul_i32 s1, s1, 3
	s_sub_i32 s0, s0, s1
	s_and_b32 s0, s0, 0xff
	s_mulk_i32 s0, 0x5600
	s_add_i32 s4, s0, 0
	v_add3_u32 v64, s4, v141, v148
	s_waitcnt vmcnt(1)
	ds_write_b128 v64, v[128:131]
	s_and_saveexec_b64 s[0:1], s[2:3]
	v_add3_u32 v64, s4, v174, v175
	ds_write_b128 v64, v[124:127] offset:128
	s_or_b64 exec, exec, s[0:1]
	v_add_u32_e32 v64, s4, v176
	v_add3_u32 v64, v64, v148, s41
	s_waitcnt vmcnt(0)
	ds_write2_b64 v64, v[132:133], v[134:135] offset1:1

.LBB0_1335:
	s_cmp_lt_i32 s56, 13
	s_cselect_b64 s[2:3], -1, 0
	s_and_b64 s[0:1], s[2:3], s[0:1]
	s_cmp_lt_i32 s58, 0x8000
	s_cselect_b64 s[2:3], -1, 0
	s_and_b64 s[0:1], s[0:1], s[2:3]
	s_andn2_b64 vcc, exec, s[0:1]
	s_cbranch_vccnz .LBB0_1347
	v_readlane_b32 s0, v244, 23
	v_readlane_b32 s1, v244, 24
	v_lshlrev_b32_e32 v1, 2, v144
	v_xor_b32_e32 v40, 4, v1
	v_xor_b32_e32 v41, 8, v1
	v_xor_b32_e32 v42, 16, v1
	v_xor_b32_e32 v43, 32, v1
	v_xor_b32_e32 v44, 64, v1
	v_xor_b32_e32 v45, 0x80, v1
	v_lshlrev_b32_e32 v2, 5, v144
	v_lshlrev_b32_e32 v3, 4, v144
	v_mov_b32_e32 v86, 0x358637bd
	s_add_u32 s2, s54, 0x2400000
	s_addc_u32 s3, s55, 0
	s_mov_b32 s10, s58
	s_add_i32 s11, s10, s75
	s_cmp_lt_i32 s11, 0x8000
	s_cselect_b32 s11, s11, s10
	s_lshl_b32 s12, s10, 11
	s_lshl_b32 s13, s11, 11
	s_add_u32 s4, s2, s12
	s_addc_u32 s5, s3, 0
	s_add_u32 s6, s2, s13
	s_addc_u32 s7, s3, 0
	global_load_dwordx4 v[24:27], v3, s[4:5]
	global_load_dwordx4 v[28:31], v3, s[4:5] offset:1024
	global_load_dwordx4 v[32:35], v3, s[6:7]
	global_load_dwordx4 v[36:39], v3, s[6:7] offset:1024
	global_load_dwordx4 v[100:103], v2, s[0:1]
	global_load_dwordx4 v[104:107], v2, s[0:1] offset:16
	global_load_dwordx4 v[108:111], v2, s[0:1] offset:2048
	global_load_dwordx4 v[112:115], v2, s[0:1] offset:2064
	s_waitcnt vmcnt(0)
.Lp12_loop:
	v_lshlrev_b32_e32 v48, 16, v24
	v_and_b32_e32 v49, 0xffff0000, v24
	v_lshlrev_b32_e32 v50, 16, v25
	v_and_b32_e32 v51, 0xffff0000, v25
	v_lshlrev_b32_e32 v52, 16, v26
	v_and_b32_e32 v53, 0xffff0000, v26
	v_lshlrev_b32_e32 v54, 16, v27
	v_and_b32_e32 v55, 0xffff0000, v27
	v_lshlrev_b32_e32 v56, 16, v28
	v_and_b32_e32 v57, 0xffff0000, v28
	v_lshlrev_b32_e32 v58, 16, v29
	v_and_b32_e32 v59, 0xffff0000, v29
	v_lshlrev_b32_e32 v60, 16, v30
	v_and_b32_e32 v61, 0xffff0000, v30
	v_lshlrev_b32_e32 v62, 16, v31
	v_and_b32_e32 v63, 0xffff0000, v31
	v_lshlrev_b32_e32 v64, 16, v32
	v_and_b32_e32 v65, 0xffff0000, v32
	v_lshlrev_b32_e32 v66, 16, v33
	v_and_b32_e32 v67, 0xffff0000, v33
	v_lshlrev_b32_e32 v68, 16, v34
	v_and_b32_e32 v69, 0xffff0000, v34
	v_lshlrev_b32_e32 v70, 16, v35
	v_and_b32_e32 v71, 0xffff0000, v35
	v_lshlrev_b32_e32 v72, 16, v36
	v_and_b32_e32 v73, 0xffff0000, v36
	v_lshlrev_b32_e32 v74, 16, v37
	v_and_b32_e32 v75, 0xffff0000, v37
	v_lshlrev_b32_e32 v76, 16, v38
	v_and_b32_e32 v77, 0xffff0000, v38
	v_lshlrev_b32_e32 v78, 16, v39
	v_and_b32_e32 v79, 0xffff0000, v39
	s_lshl_b32 s12, s10, 12
	s_lshl_b32 s13, s11, 12
	s_add_u32 s14, s52, s12
	s_addc_u32 s15, s53, 0
	s_add_u32 s16, s52, s13
	s_addc_u32 s17, s53, 0
	s_add_i32 s10, s10, s75
	s_add_i32 s10, s10, s75
	s_cmp_lt_i32 s10, 0x8000
	s_cselect_b32 s18, 1, 0
	s_cbranch_scc0 .Lp12_nonext
	s_add_i32 s11, s10, s75
	s_cmp_lt_i32 s11, 0x8000
	s_cselect_b32 s11, s11, s10
	s_lshl_b32 s12, s10, 11
	s_lshl_b32 s13, s11, 11
	s_add_u32 s4, s2, s12
	s_addc_u32 s5, s3, 0
	s_add_u32 s6, s2, s13
	s_addc_u32 s7, s3, 0
	global_load_dwordx4 v[24:27], v3, s[4:5]
	global_load_dwordx4 v[28:31], v3, s[4:5] offset:1024
	global_load_dwordx4 v[32:35], v3, s[6:7]
	global_load_dwordx4 v[36:39], v3, s[6:7] offset:1024
.Lp12_nonext:
	v_mul_f32_e32 v80, v48, v48
	v_mul_f32_e32 v82, v64, v64
	v_mul_f32_e32 v81, v49, v49
	v_mul_f32_e32 v83, v65, v65
	v_fmac_f32_e32 v80, v50, v50
	v_fmac_f32_e32 v82, v66, v66
	v_fmac_f32_e32 v81, v51, v51
	v_fmac_f32_e32 v83, v67, v67
	v_fmac_f32_e32 v80, v52, v52
	v_fmac_f32_e32 v82, v68, v68
	v_fmac_f32_e32 v81, v53, v53
	v_fmac_f32_e32 v83, v69, v69
	v_fmac_f32_e32 v80, v54, v54
	v_fmac_f32_e32 v82, v70, v70
	v_fmac_f32_e32 v81, v55, v55
	v_fmac_f32_e32 v83, v71, v71
	v_fmac_f32_e32 v80, v56, v56
	v_fmac_f32_e32 v82, v72, v72
	v_fmac_f32_e32 v81, v57, v57
	v_fmac_f32_e32 v83, v73, v73
	v_fmac_f32_e32 v80, v58, v58
	v_fmac_f32_e32 v82, v74, v74
	v_fmac_f32_e32 v81, v59, v59
	v_fmac_f32_e32 v83, v75, v75
	v_fmac_f32_e32 v80, v60, v60
	v_fmac_f32_e32 v82, v76, v76
	v_fmac_f32_e32 v81, v61, v61
	v_fmac_f32_e32 v83, v77, v77
	v_fmac_f32_e32 v80, v62, v62
	v_fmac_f32_e32 v82, v78, v78
	v_fmac_f32_e32 v81, v63, v63
	v_fmac_f32_e32 v83, v79, v79
	v_add_f32_e32 v80, v80, v81
	v_add_f32_e32 v82, v82, v83
	ds_bpermute_b32 v84, v40, v80
	ds_bpermute_b32 v85, v40, v82
	s_waitcnt lgkmcnt(1)
	v_add_f32_e32 v80, v80, v84
	s_waitcnt lgkmcnt(0)
	v_add_f32_e32 v82, v82, v85
	ds_bpermute_b32 v84, v41, v80
	ds_bpermute_b32 v85, v41, v82
	s_waitcnt lgkmcnt(1)
	v_add_f32_e32 v80, v80, v84
	s_waitcnt lgkmcnt(0)
	v_add_f32_e32 v82, v82, v85
	ds_bpermute_b32 v84, v42, v80
	ds_bpermute_b32 v85, v42, v82
	s_waitcnt lgkmcnt(1)
	v_add_f32_e32 v80, v80, v84
	s_waitcnt lgkmcnt(0)
	v_add_f32_e32 v82, v82, v85
	ds_bpermute_b32 v84, v43, v80
	ds_bpermute_b32 v85, v43, v82
	s_waitcnt lgkmcnt(1)
	v_add_f32_e32 v80, v80, v84
	s_waitcnt lgkmcnt(0)
	v_add_f32_e32 v82, v82, v85
	ds_bpermute_b32 v84, v44, v80
	ds_bpermute_b32 v85, v44, v82
	s_waitcnt lgkmcnt(1)
	v_add_f32_e32 v80, v80, v84
	s_waitcnt lgkmcnt(0)
	v_add_f32_e32 v82, v82, v85
	ds_bpermute_b32 v84, v45, v80
	ds_bpermute_b32 v85, v45, v82
	s_waitcnt lgkmcnt(1)
	v_add_f32_e32 v80, v80, v84
	s_waitcnt lgkmcnt(0)
	v_add_f32_e32 v82, v82, v85
	v_fmamk_f32 v80, v80, 0x3a800000, v86
	v_fmamk_f32 v82, v82, 0x3a800000, v86
	v_rsq_f32_e32 v80, v80
	v_rsq_f32_e32 v82, v82
	s_nop 0
	v_mul_f32_e32 v48, v48, v80
	v_mul_f32_e32 v64, v64, v82
	v_mul_f32_e32 v49, v49, v80
	v_mul_f32_e32 v65, v65, v82
	v_mul_f32_e32 v50, v50, v80
	v_mul_f32_e32 v66, v66, v82
	v_mul_f32_e32 v51, v51, v80
	v_mul_f32_e32 v67, v67, v82
	v_mul_f32_e32 v52, v52, v80
	v_mul_f32_e32 v68, v68, v82
	v_mul_f32_e32 v53, v53, v80
	v_mul_f32_e32 v69, v69, v82
	v_mul_f32_e32 v54, v54, v80
	v_mul_f32_e32 v70, v70, v82
	v_mul_f32_e32 v55, v55, v80
	v_mul_f32_e32 v71, v71, v82
	v_mul_f32_e32 v56, v56, v80
	v_mul_f32_e32 v72, v72, v82
	v_mul_f32_e32 v57, v57, v80
	v_mul_f32_e32 v73, v73, v82
	v_mul_f32_e32 v58, v58, v80
	v_mul_f32_e32 v74, v74, v82
	v_mul_f32_e32 v59, v59, v80
	v_mul_f32_e32 v75, v75, v82
	v_mul_f32_e32 v60, v60, v80
	v_mul_f32_e32 v76, v76, v82
	v_mul_f32_e32 v61, v61, v80
	v_mul_f32_e32 v77, v77, v82
	v_mul_f32_e32 v62, v62, v80
	v_mul_f32_e32 v78, v78, v82
	v_mul_f32_e32 v63, v63, v80
	v_mul_f32_e32 v79, v79, v82
	v_mul_f32_e32 v48, v48, v100
	v_mul_f32_e32 v64, v64, v100
	v_mul_f32_e32 v49, v49, v101
	v_mul_f32_e32 v65, v65, v101
	v_mul_f32_e32 v50, v50, v102
	v_mul_f32_e32 v66, v66, v102
	v_mul_f32_e32 v51, v51, v103
	v_mul_f32_e32 v67, v67, v103
	v_mul_f32_e32 v52, v52, v104
	v_mul_f32_e32 v68, v68, v104
	v_mul_f32_e32 v53, v53, v105
	v_mul_f32_e32 v69, v69, v105
	v_mul_f32_e32 v54, v54, v106
	v_mul_f32_e32 v70, v70, v106
	v_mul_f32_e32 v55, v55, v107
	v_mul_f32_e32 v71, v71, v107
	v_mul_f32_e32 v56, v56, v108
	v_mul_f32_e32 v72, v72, v108
	v_mul_f32_e32 v57, v57, v109
	v_mul_f32_e32 v73, v73, v109
	v_mul_f32_e32 v58, v58, v110
	v_mul_f32_e32 v74, v74, v110
	v_mul_f32_e32 v59, v59, v111
	v_mul_f32_e32 v75, v75, v111
	v_mul_f32_e32 v60, v60, v112
	v_mul_f32_e32 v76, v76, v112
	v_mul_f32_e32 v61, v61, v113
	v_mul_f32_e32 v77, v77, v113
	v_mul_f32_e32 v62, v62, v114
	v_mul_f32_e32 v78, v78, v114
	v_mul_f32_e32 v63, v63, v115
	v_mul_f32_e32 v79, v79, v115
	global_store_dwordx4 v2, v[48:51], s[14:15]
	global_store_dwordx4 v2, v[52:55], s[14:15] offset:16
	global_store_dwordx4 v2, v[56:59], s[14:15] offset:2048
	global_store_dwordx4 v2, v[60:63], s[14:15] offset:2064
	global_store_dwordx4 v2, v[64:67], s[16:17]
	global_store_dwordx4 v2, v[68:71], s[16:17] offset:16
	global_store_dwordx4 v2, v[72:75], s[16:17] offset:2048
	global_store_dwordx4 v2, v[76:79], s[16:17] offset:2064
	s_cmp_lg_u32 s18, 0
	s_cbranch_scc0 .LBB0_1347
	s_waitcnt vmcnt(8)
	s_branch .Lp12_loop

	.amdhsa_kernel _Z6mk_fwd4Args
		.amdhsa_group_segment_fixed_size 0
		.amdhsa_private_segment_fixed_size 0
		.amdhsa_kernarg_size 480
		.amdhsa_user_sgpr_count 2
		.amdhsa_user_sgpr_dispatch_ptr 0
		.amdhsa_user_sgpr_queue_ptr 0
		.amdhsa_user_sgpr_kernarg_segment_ptr 1
		.amdhsa_user_sgpr_dispatch_id 0
		.amdhsa_user_sgpr_kernarg_preload_length 0
		.amdhsa_user_sgpr_kernarg_preload_offset 0
		.amdhsa_user_sgpr_private_segment_size 0
		.amdhsa_uses_dynamic_stack 0
		.amdhsa_enable_private_segment 0
		.amdhsa_system_sgpr_workgroup_id_x 1
		.amdhsa_system_sgpr_workgroup_id_y 0
		.amdhsa_system_sgpr_workgroup_id_z 0
		.amdhsa_system_sgpr_workgroup_info 0
		.amdhsa_system_vgpr_workitem_id 2
		.amdhsa_next_free_vgpr 247
		.amdhsa_next_free_sgpr 98
		.amdhsa_accum_offset 248
		.amdhsa_reserve_vcc 1
		.amdhsa_float_round_mode_32 0
		.amdhsa_float_round_mode_16_64 0
		.amdhsa_float_denorm_mode_32 3
		.amdhsa_float_denorm_mode_16_64 3
		.amdhsa_dx10_clamp 1
		.amdhsa_ieee_mode 1
		.amdhsa_fp16_overflow 0
		.amdhsa_tg_split 0
		.amdhsa_exception_fp_ieee_invalid_op 0
		.amdhsa_exception_fp_denorm_src 0
		.amdhsa_exception_fp_ieee_div_zero 0
		.amdhsa_exception_fp_ieee_overflow 0
		.amdhsa_exception_fp_ieee_underflow 0
		.amdhsa_exception_fp_ieee_inexact 0
		.amdhsa_exception_int_div_zero 0
	.end_amdhsa_kernel

amdhsa.kernels:
  - .agpr_count:     0
    .args:
      - .offset:         0
        .size:           224
        .value_kind:     by_value
      - .offset:         224
        .size:           4
        .value_kind:     hidden_block_count_x
      - .offset:         228
        .size:           4
        .value_kind:     hidden_block_count_y
      - .offset:         232
        .size:           4
        .value_kind:     hidden_block_count_z
      - .offset:         236
        .size:           2
        .value_kind:     hidden_group_size_x
      - .offset:         238
        .size:           2
        .value_kind:     hidden_group_size_y
      - .offset:         240
        .size:           2
        .value_kind:     hidden_group_size_z
      - .offset:         242
        .size:           2
        .value_kind:     hidden_remainder_x
      - .offset:         244
        .size:           2
        .value_kind:     hidden_remainder_y
      - .offset:         246
        .size:           2
        .value_kind:     hidden_remainder_z
      - .offset:         264
        .size:           8
        .value_kind:     hidden_global_offset_x
      - .offset:         272
        .size:           8
        .value_kind:     hidden_global_offset_y
      - .offset:         280
        .size:           8
        .value_kind:     hidden_global_offset_z
      - .offset:         288
        .size:           2
        .value_kind:     hidden_grid_dims
      - .offset:         312
        .size:           8
        .value_kind:     hidden_multigrid_sync_arg
      - .offset:         344
        .size:           4
        .value_kind:     hidden_dynamic_lds_size
    .group_segment_fixed_size: 0
    .kernarg_segment_align: 8
    .kernarg_segment_size: 480
    .language:       OpenCL C
    .language_version:
      - 2
      - 0
    .max_flat_workgroup_size: 512
    .name:           _Z6mk_fwd4Args
    .private_segment_fixed_size: 0
    .sgpr_count:     104
    .sgpr_spill_count: 30
    .symbol:         _Z6mk_fwd4Args.kd
    .uniform_work_group_size: 1
    .uses_dynamic_stack: false
    .vgpr_count:     247
    .vgpr_spill_count: 0
    .wavefront_size: 64
